# row-sum MFMAs moved two instructions later for extra VALU->MFMA operand wait-state margin
# speedup vs baseline: 1.0053x; 1.0053x over previous
.LBB0_590:
	s_waitcnt lgkmcnt(2)
	v_mfma_f32_32x32x16_bf16 v[16:31], v[128:131], v[48:51], v[16:31]
	ds_read_b64_tr_b16 v[56:57], v15 offset:2048
	ds_read_b64_tr_b16 v[58:59], v15 offset:3072
	ds_read_b64_tr_b16 v[48:49], v15 offset:2560
	ds_read_b64_tr_b16 v[50:51], v15 offset:3584
	v_mfma_f32_16x16x32_bf16 v[144:147], v[2:5], v[140:143], v[144:147]
	v_exp_f32_e32 v96, v96
	v_exp_f32_e32 v97, v97
	v_exp_f32_e32 v98, v98
	v_exp_f32_e32 v99, v99
	s_waitcnt lgkmcnt(4)
	v_mfma_f32_32x32x16_bf16 v[32:47], v[128:131], v[52:55], v[32:47]
	ds_read_b64_tr_b16 v[52:53], v15 offset:4096
	ds_read_b64_tr_b16 v[54:55], v15 offset:5120
	v_exp_f32_e32 v100, v100
	v_exp_f32_e32 v101, v101
	v_exp_f32_e32 v102, v102
	v_exp_f32_e32 v103, v103
	s_waitcnt lgkmcnt(4)
	v_mfma_f32_32x32x16_bf16 v[16:31], v[10:13], v[56:59], v[16:31]
	ds_read_b64_tr_b16 v[56:57], v15 offset:4608
	ds_read_b64_tr_b16 v[58:59], v15 offset:5632
	v_exp_f32_e32 v104, v104
	v_exp_f32_e32 v105, v105
	v_exp_f32_e32 v106, v106
	v_exp_f32_e32 v107, v107
	s_waitcnt lgkmcnt(4)
	v_mfma_f32_32x32x16_bf16 v[32:47], v[10:13], v[48:51], v[32:47]
	ds_read_b64_tr_b16 v[10:11], v15 offset:6144
	ds_read_b64_tr_b16 v[12:13], v15 offset:7168
	v_exp_f32_e32 v108, v108
	v_exp_f32_e32 v109, v109
	v_exp_f32_e32 v110, v110
	v_exp_f32_e32 v111, v111
	s_waitcnt lgkmcnt(4)
	v_mfma_f32_32x32x16_bf16 v[16:31], v[6:9], v[52:55], v[16:31]
	ds_read_b64_tr_b16 v[48:49], v15 offset:6656
	ds_read_b64_tr_b16 v[50:51], v15 offset:7680
	v_exp_f32_e32 v80, v80
	v_exp_f32_e32 v81, v81
	v_exp_f32_e32 v82, v82
	v_exp_f32_e32 v83, v83
	s_waitcnt lgkmcnt(4)
	v_mfma_f32_32x32x16_bf16 v[32:47], v[6:9], v[56:59], v[32:47]
	v_exp_f32_e32 v84, v84
	v_exp_f32_e32 v85, v85
	v_exp_f32_e32 v86, v86
	v_exp_f32_e32 v87, v87
	s_waitcnt lgkmcnt(2)
	v_mfma_f32_32x32x16_bf16 v[16:31], v[2:5], v[10:13], v[16:31]
	v_exp_f32_e32 v88, v88
	v_exp_f32_e32 v89, v89
	v_exp_f32_e32 v90, v90
	v_exp_f32_e32 v91, v91
	s_waitcnt lgkmcnt(0)
	v_mfma_f32_32x32x16_bf16 v[32:47], v[2:5], v[48:51], v[32:47]
	v_exp_f32_e32 v92, v92
	v_exp_f32_e32 v93, v93
	v_exp_f32_e32 v94, v94
	v_exp_f32_e32 v95, v95
	s_add_i32 s12, s8, -4
	s_add_i32 s13, s8, 1
	s_cmp_gt_i32 s8, 3
	s_cselect_b32 s12, s12, s13
	v_lshl_add_u32 v6, s12, 13, v135
	ds_read_b128 v[2:5], v6
	ds_read_b128 v[6:9], v6 offset:512
	s_cmp_lg_u32 s8, 4
	s_cselect_b32 s54, s13, 0
	v_lshl_add_u32 v15, s54, 13, v135
	v_lshl_add_u32 v128, s8, 14, v1
	s_waitcnt lgkmcnt(1)
	v_mfma_f32_32x32x16_bf16 v[64:79], v[2:5], v[124:127], 0
	ds_read_b128 v[10:13], v15 offset:2048
	v_cvt_pk_bf16_f32 v2, v96, v97
	v_cvt_pk_bf16_f32 v3, v98, v99
	s_nop 0
	ds_read_b128 v[96:99], v15 offset:2560
	v_cvt_pk_bf16_f32 v4, v100, v101
	s_waitcnt lgkmcnt(2)
	v_mfma_f32_32x32x16_bf16 v[48:63], v[6:9], v[124:127], 0
	v_cvt_pk_bf16_f32 v5, v102, v103
	s_waitcnt lgkmcnt(1)
	v_mfma_f32_32x32x16_bf16 v[64:79], v[10:13], v[120:123], v[64:79]
	ds_read_b128 v[6:9], v15 offset:4096
	v_mfma_f32_16x16x32_bf16 v[144:147], v[2:5], v[140:143], v[144:147]
	v_cvt_pk_bf16_f32 v10, v104, v105
	v_cvt_pk_bf16_f32 v11, v106, v107
	s_waitcnt lgkmcnt(1)
	v_mfma_f32_32x32x16_bf16 v[48:63], v[96:99], v[120:123], v[48:63]
	ds_read_b128 v[100:103], v15 offset:4608
	v_cvt_pk_bf16_f32 v12, v108, v109
	v_cvt_pk_bf16_f32 v13, v110, v111
	s_waitcnt lgkmcnt(1)
	v_mfma_f32_32x32x16_bf16 v[64:79], v[6:9], v[116:119], v[64:79]
	ds_read_b128 v[96:99], v15 offset:6144
	v_mfma_f32_16x16x32_bf16 v[144:147], v[10:13], v[140:143], v[144:147]
	v_cvt_pk_bf16_f32 v6, v80, v81
	v_cvt_pk_bf16_f32 v7, v82, v83
	s_waitcnt lgkmcnt(1)
	v_mfma_f32_32x32x16_bf16 v[48:63], v[100:103], v[116:119], v[48:63]
	ds_read_b128 v[80:83], v15 offset:6656
	v_cvt_pk_bf16_f32 v8, v84, v85
	v_cvt_pk_bf16_f32 v9, v86, v87
	s_waitcnt lgkmcnt(1)
	v_mfma_f32_32x32x16_bf16 v[64:79], v[96:99], v[112:115], v[64:79]
	v_cvt_pk_bf16_f32 v84, v88, v89
	v_cvt_pk_bf16_f32 v85, v90, v91
	v_mfma_f32_16x16x32_bf16 v[144:147], v[6:9], v[140:143], v[144:147]
	ds_read_b64_tr_b16 v[88:89], v128
	ds_read_b64_tr_b16 v[90:91], v128 offset:1024
	s_waitcnt lgkmcnt(2)
	v_mfma_f32_32x32x16_bf16 v[48:63], v[80:83], v[112:115], v[48:63]
	v_cvt_pk_bf16_f32 v86, v92, v93
	v_cvt_pk_bf16_f32 v87, v94, v95
	ds_read_b64_tr_b16 v[80:81], v128 offset:512
	ds_read_b64_tr_b16 v[82:83], v128 offset:1536
	s_waitcnt lgkmcnt(2)
	v_mfma_f32_32x32x16_bf16 v[16:31], v[2:5], v[88:91], v[16:31]
	ds_read_b64_tr_b16 v[92:93], v128 offset:2048
	ds_read_b64_tr_b16 v[94:95], v128 offset:3072
	ds_read_b64_tr_b16 v[88:89], v128 offset:2560
	ds_read_b64_tr_b16 v[90:91], v128 offset:3584
	v_mfma_f32_16x16x32_bf16 v[144:147], v[84:87], v[140:143], v[144:147]
	v_exp_f32_e32 v64, v64
	v_exp_f32_e32 v65, v65
	v_exp_f32_e32 v66, v66
	v_exp_f32_e32 v67, v67
	s_waitcnt lgkmcnt(4)
	v_mfma_f32_32x32x16_bf16 v[32:47], v[2:5], v[80:83], v[32:47]
	ds_read_b64_tr_b16 v[2:3], v128 offset:4096
	ds_read_b64_tr_b16 v[4:5], v128 offset:5120
	v_exp_f32_e32 v68, v68
	v_exp_f32_e32 v69, v69
	v_exp_f32_e32 v70, v70
	v_exp_f32_e32 v71, v71
	s_waitcnt lgkmcnt(4)
	v_mfma_f32_32x32x16_bf16 v[16:31], v[10:13], v[92:95], v[16:31]
	ds_read_b64_tr_b16 v[80:81], v128 offset:4608
	ds_read_b64_tr_b16 v[82:83], v128 offset:5632
	v_exp_f32_e32 v72, v72
	v_exp_f32_e32 v73, v73
	v_exp_f32_e32 v74, v74
	v_exp_f32_e32 v75, v75
	s_waitcnt lgkmcnt(4)
	v_mfma_f32_32x32x16_bf16 v[32:47], v[10:13], v[88:91], v[32:47]
	ds_read_b64_tr_b16 v[10:11], v128 offset:6144
	ds_read_b64_tr_b16 v[12:13], v128 offset:7168
	v_exp_f32_e32 v76, v76
	v_exp_f32_e32 v77, v77
	v_exp_f32_e32 v78, v78
	v_exp_f32_e32 v79, v79
	s_waitcnt lgkmcnt(4)
	v_mfma_f32_32x32x16_bf16 v[16:31], v[6:9], v[2:5], v[16:31]
	ds_read_b64_tr_b16 v[2:3], v128 offset:6656
	ds_read_b64_tr_b16 v[4:5], v128 offset:7680
	v_exp_f32_e32 v48, v48
	v_exp_f32_e32 v49, v49
	v_exp_f32_e32 v50, v50
	v_exp_f32_e32 v51, v51
	s_waitcnt lgkmcnt(4)
	v_mfma_f32_32x32x16_bf16 v[32:47], v[6:9], v[80:83], v[32:47]
	v_exp_f32_e32 v52, v52
	v_exp_f32_e32 v53, v53
	v_exp_f32_e32 v54, v54
	v_exp_f32_e32 v55, v55
	s_waitcnt lgkmcnt(2)
	v_mfma_f32_32x32x16_bf16 v[16:31], v[84:87], v[10:13], v[16:31]
	v_exp_f32_e32 v56, v56
	v_exp_f32_e32 v57, v57
	v_exp_f32_e32 v58, v58
	v_exp_f32_e32 v59, v59
	s_waitcnt lgkmcnt(0)
	v_mfma_f32_32x32x16_bf16 v[32:47], v[84:87], v[2:5], v[32:47]
	v_exp_f32_e32 v60, v60
	v_exp_f32_e32 v61, v61
	v_exp_f32_e32 v62, v62
	v_exp_f32_e32 v63, v63
	s_add_i32 s8, s54, 1
	s_cmp_lg_u32 s54, 4
	s_cselect_b32 s8, s8, 0
	s_add_u32 s6, s6, 0x4000
	s_addc_u32 s7, s7, 0
	s_add_u32 s40, s40, 0x4000
	s_waitcnt vmcnt(0) lgkmcnt(0)
	s_barrier
	s_addc_u32 s41, s41, 0
	s_add_i32 s49, s49, 2
	s_cmp_lt_u32 s51, s50
	s_cbranch_scc0 .LBB0_596
.LBB0_591:
	v_lshl_add_u32 v136, s8, 13, v135
	ds_read_b128 v[2:5], v136
	ds_read_b128 v[6:9], v136 offset:512
	s_lshl_b32 s12, s54, 14
	v_add_u32_e32 v15, s12, v1
	s_waitcnt lgkmcnt(1)
	v_mfma_f32_32x32x16_bf16 v[96:111], v[2:5], v[124:127], 0
	ds_read_b128 v[10:13], v136 offset:2048
	v_cvt_pk_bf16_f32 v128, v64, v65
	v_cvt_pk_bf16_f32 v129, v66, v67
	s_waitcnt lgkmcnt(1)
	v_mfma_f32_32x32x16_bf16 v[80:95], v[6:9], v[124:127], 0
	ds_read_b128 v[2:5], v136 offset:2560
	v_cvt_pk_bf16_f32 v130, v68, v69
	v_cvt_pk_bf16_f32 v131, v70, v71
	s_waitcnt lgkmcnt(1)
	v_mfma_f32_32x32x16_bf16 v[96:111], v[10:13], v[120:123], v[96:111]
	ds_read_b128 v[6:9], v136 offset:4096
	v_mfma_f32_16x16x32_bf16 v[144:147], v[128:131], v[140:143], v[144:147]
	v_cvt_pk_bf16_f32 v10, v72, v73
	v_cvt_pk_bf16_f32 v11, v74, v75
	s_waitcnt lgkmcnt(1)
	v_mfma_f32_32x32x16_bf16 v[80:95], v[2:5], v[120:123], v[80:95]
	ds_read_b128 v[64:67], v136 offset:4608
	v_cvt_pk_bf16_f32 v12, v76, v77
	v_cvt_pk_bf16_f32 v13, v78, v79
	s_waitcnt lgkmcnt(1)
	v_mfma_f32_32x32x16_bf16 v[96:111], v[6:9], v[116:119], v[96:111]
	ds_read_b128 v[2:5], v136 offset:6144
	v_mfma_f32_16x16x32_bf16 v[144:147], v[10:13], v[140:143], v[144:147]
	v_cvt_pk_bf16_f32 v6, v48, v49
	v_cvt_pk_bf16_f32 v7, v50, v51
	s_waitcnt lgkmcnt(1)
	v_mfma_f32_32x32x16_bf16 v[80:95], v[64:67], v[116:119], v[80:95]
	ds_read_b128 v[68:71], v136 offset:6656
	v_cvt_pk_bf16_f32 v8, v52, v53
	v_cvt_pk_bf16_f32 v9, v54, v55
	s_waitcnt lgkmcnt(1)
	v_mfma_f32_32x32x16_bf16 v[96:111], v[2:5], v[112:115], v[96:111]
	v_cvt_pk_bf16_f32 v2, v56, v57
	v_cvt_pk_bf16_f32 v3, v58, v59
	v_mfma_f32_16x16x32_bf16 v[144:147], v[6:9], v[140:143], v[144:147]
	ds_read_b64_tr_b16 v[48:49], v15
	ds_read_b64_tr_b16 v[50:51], v15 offset:1024
	s_waitcnt lgkmcnt(2)
	v_mfma_f32_32x32x16_bf16 v[80:95], v[68:71], v[112:115], v[80:95]
	v_cvt_pk_bf16_f32 v4, v60, v61
	v_cvt_pk_bf16_f32 v5, v62, v63
	ds_read_b64_tr_b16 v[52:53], v15 offset:512
	ds_read_b64_tr_b16 v[54:55], v15 offset:1536
	s_add_i32 s51, s49, -1
	s_cmp_ge_u32 s51, s48
	s_cbranch_scc1 .LBB0_593
	s_add_u32 s12, s40, 0xffffe000
	s_addc_u32 s13, s41, -1
	s_cmp_gt_i32 s8, 2
	s_cselect_b32 s54, -3, 2
	s_add_i32 s54, s54, s8
	s_lshl_b32 s55, s54, 13
	s_add_i32 s55, s55, s46
	s_mov_b32 s56, m0
	s_mov_b32 m0, s55
	s_nop 0
	global_load_lds_dwordx4 v134, s[12:13]
	s_mov_b32 m0, s56
	s_add_u32 s12, s6, 0xffffe000
	s_addc_u32 s13, s7, -1
	s_lshl_b32 s54, s54, 14
	s_add_i32 s54, s54, s47
	s_mov_b32 s55, m0
	s_mov_b32 m0, s54
	s_nop 0
	global_load_lds_dwordx4 v134, s[12:13]
	s_mov_b32 m0, s55
